# v25
# speedup vs baseline: 1.0235x; 1.0050x over previous
.LBB0_381:
	s_or_b64 exec, exec, s[2:3]
	s_barrier
	s_mov_b32 s0, 0x18000
	v_ashrrev_i32_e32 v0, 6, v138
	v_add_u32_e32 v96, s70, v0
	v_cmp_gt_i32_e32 vcc, s0, v96
	s_and_saveexec_b64 s[0:1], vcc
	s_cbranch_execz .LBB0_399
	v_and_b32_e32 v2, 64, v139
	v_and_b32_e32 v1, 31, v138
	v_xor_b32_e32 v0, 32, v139
	v_add_u32_e32 v2, 64, v2
	v_lshlrev_b32_e32 v98, 4, v1
	v_mov_b32_e32 v99, 0
	v_cmp_lt_i32_e32 vcc, v0, v2
	s_waitcnt vmcnt(5)
	v_lshl_add_u64 v[4:5], s[80:81], 0, v[98:99]
	s_mov_b64 s[2:3], 0x18000000
	v_cndmask_b32_e32 v0, v139, v0, vcc
	v_lshlrev_b32_e32 v185, 2, v0
	v_bfe_u32 v0, v138, 5, 1
	v_lshl_add_u64 v[104:105], v[4:5], 0, s[2:3]
	s_mov_b64 s[2:3], 0x18800000
	v_and_b32_e32 v184, 63, v138
	v_sub_u32_e32 v100, 0, v0
	v_lshlrev_b32_e32 v0, 4, v0
	v_lshlrev_b32_e32 v2, 7, v1
	v_mov_b32_e32 v3, v99
	v_lshl_add_u64 v[108:109], v[4:5], 0, s[2:3]
	v_add_u32_e32 v208, 0x18000000, v98
	v_add_u32_e32 v209, 0x18800000, v98
	s_add_u32 s2, s80, 0x21000000
	v_cmp_gt_u32_e64 s[0:1], 32, v184
	v_lshl_add_u64 v[102:103], s[78:79], 0, v[2:3]
	v_lshl_add_u64 v[106:107], s[68:69], 0, v[2:3]
	s_addc_u32 s3, s81, 0
	v_mov_b32_e32 v101, v100
	s_mov_b64 s[4:5], 0
	v_mov_b32_e32 v186, 0x358637bd
	s_mov_b32 s12, 0x800000
	s_mov_b32 s13, 0x378e98ab
	s_mov_b32 s14, 0x3b7cd369
	s_mov_b32 s15, 0xbcc618b2
	s_mov_b32 s16, 0x3dda74e4
	s_mov_b32 s17, 0x3f228afd
	s_mov_b32 s18, 0x3e03c728
	s_mov_b32 s19, 0xbfb8aa3b
	s_mov_b32 s20, 0x42ce8ed0
	s_mov_b32 s21, 0xc2b17218
	v_mov_b32_e32 v187, 0x3ba10414
	s_brev_b32 s22, -2
	v_lshlrev_b32_e32 v110, 2, v0
	s_mov_b32 s23, 0x17fff
	v_mov_b32_e32 v188, 0xb9c68948
	v_mov_b32_e32 v189, 0x7f800000
	s_branch .LBB0_384

.LBB0_386:
	v_or_b32_e32 v98, s10, v184
	v_lshlrev_b64 v[0:1], 2, v[98:99]
	v_lshl_add_u64 v[2:3], v[146:147], 0, v[0:1]
	global_load_dword v4, v[2:3], off
	v_lshl_add_u64 v[2:3], v[148:149], 0, v[0:1]
	v_lshl_add_u64 v[0:1], v[150:151], 0, v[0:1]
	global_load_dword v72, v[2:3], off
	global_load_dword v64, v[0:1], off
	v_mov_b32_e32 v65, 0
	s_waitcnt vmcnt(2)
	v_and_b32_e32 v97, 0x3fff, v4
	s_nop 0
	v_readlane_b32 s6, v97, 0
	v_readlane_b32 s7, v97, 1
	v_readlane_b32 s10, v97, 2
	v_readlane_b32 s11, v97, 3
	v_readlane_b32 s24, v97, 4
	v_readlane_b32 s25, v97, 5
	v_readlane_b32 s26, v97, 6
	v_readlane_b32 s27, v97, 7
	v_readlane_b32 s28, v97, 8
	v_readlane_b32 s29, v97, 9
	v_readlane_b32 s30, v97, 10
	v_readlane_b32 s31, v97, 11
	v_readlane_b32 s33, v97, 12
	v_readlane_b32 s34, v97, 13
	v_readlane_b32 s35, v97, 14
	v_readlane_b32 s36, v97, 15
	v_mov_b32_e32 v0, s7
	v_mov_b32_e32 v1, s6
	v_mov_b32_e32 v2, s11
	v_mov_b32_e32 v3, s10
	v_mov_b32_e32 v4, s25
	v_mov_b32_e32 v5, s24
	v_mov_b32_e32 v6, s27
	v_mov_b32_e32 v7, s26
	v_mov_b32_e32 v8, s29
	v_mov_b32_e32 v9, s28
	v_mov_b32_e32 v10, s31
	v_mov_b32_e32 v11, s30
	v_mov_b32_e32 v12, s34
	v_mov_b32_e32 v13, s33
	v_mov_b32_e32 v14, s36
	v_mov_b32_e32 v15, s35
	v_cndmask_b32_e64 v0, v0, v1, s[0:1]
	v_cndmask_b32_e64 v2, v2, v3, s[0:1]
	v_cndmask_b32_e64 v4, v4, v5, s[0:1]
	v_cndmask_b32_e64 v6, v6, v7, s[0:1]
	v_cndmask_b32_e64 v8, v8, v9, s[0:1]
	v_cndmask_b32_e64 v10, v10, v11, s[0:1]
	v_cndmask_b32_e64 v12, v12, v13, s[0:1]
	v_cndmask_b32_e64 v14, v14, v15, s[0:1]
	v_lshl_add_u32 v16, v0, 9, v208
	v_lshl_add_u32 v18, v2, 9, v208
	v_lshl_add_u32 v20, v4, 9, v208
	v_lshl_add_u32 v22, v6, 9, v208
	v_lshl_add_u32 v24, v8, 9, v208
	v_lshl_add_u32 v26, v10, 9, v208
	v_lshl_add_u32 v28, v12, 9, v208
	v_lshl_add_u32 v30, v14, 9, v208
	global_load_dwordx4 v[0:3], v16, s[80:81]
	global_load_dwordx4 v[4:7], v18, s[80:81]
	global_load_dwordx4 v[8:11], v20, s[80:81]
	global_load_dwordx4 v[12:15], v22, s[80:81]
	s_nop 0
	global_load_dwordx4 v[16:19], v24, s[80:81]
	global_load_dwordx4 v[20:23], v26, s[80:81]
	s_nop 0
	global_load_dwordx4 v[24:27], v28, s[80:81]
	s_nop 0
	global_load_dwordx4 v[28:31], v30, s[80:81]
	s_mov_b64 s[10:11], -1
	s_xor_b64 s[6:7], s[8:9], -1
	s_mov_b32 s24, 0
	s_branch .LBB0_388

.LBB0_388:
	s_waitcnt vmcnt(7)
	v_cvt_scalef32_pk_f32_fp4 v[66:67], v0, 1.0
	v_pk_fma_f32 v[66:67], v[114:115], v[66:67], 0 op_sel_hi:[1,1,0]
	v_cvt_scalef32_pk_f32_fp4 v[68:69], v0, 1.0 op_sel:[1,0,0]
	v_cvt_scalef32_pk_f32_fp4 v[70:71], v0, 1.0 op_sel:[0,1,0]
	v_pk_fma_f32 v[68:69], v[116:117], v[68:69], 0 op_sel_hi:[1,1,0]
	v_pk_fma_f32 v[66:67], v[118:119], v[70:71], v[66:67]
	v_cvt_scalef32_pk_f32_fp4 v[70:71], v0, 1.0 op_sel:[1,1,0]
	s_or_b32 s38, s24, 16
	s_or_b32 s39, s24, 17
	v_pk_fma_f32 v[68:69], v[120:121], v[70:71], v[68:69]
	v_cvt_scalef32_pk_f32_fp4 v[70:71], v1, 1.0
	s_xor_b64 s[8:9], s[10:11], -1
	v_readlane_b32 s10, v97, s38
	v_readlane_b32 s11, v97, s39
	s_or_b32 s36, s24, 18
	s_or_b32 s37, s24, 19
	v_pk_fma_f32 v[66:67], v[122:123], v[70:71], v[66:67]
	v_cvt_scalef32_pk_f32_fp4 v[70:71], v1, 1.0 op_sel:[1,0,0]
	v_mov_b32_e32 v32, s11
	v_mov_b32_e32 v33, s10
	v_readlane_b32 s10, v97, s36
	v_readlane_b32 s11, v97, s37
	v_pk_fma_f32 v[68:69], v[124:125], v[70:71], v[68:69]
	v_cvt_scalef32_pk_f32_fp4 v[70:71], v1, 1.0 op_sel:[0,1,0]
	v_cndmask_b32_e64 v32, v32, v33, s[0:1]
	v_mov_b32_e32 v34, s11
	v_mov_b32_e32 v35, s10
	v_pk_fma_f32 v[66:67], v[126:127], v[70:71], v[66:67]
	v_cvt_scalef32_pk_f32_fp4 v[70:71], v1, 1.0 op_sel:[1,1,0]
	v_cndmask_b32_e64 v34, v34, v35, s[0:1]
	v_pk_fma_f32 v[68:69], v[128:129], v[70:71], v[68:69]
	v_cvt_scalef32_pk_f32_fp4 v[70:71], v2, 1.0
	s_or_b32 s34, s24, 20
	s_or_b32 s35, s24, 21
	v_pk_fma_f32 v[66:67], v[130:131], v[70:71], v[66:67]
	v_cvt_scalef32_pk_f32_fp4 v[70:71], v2, 1.0 op_sel:[1,0,0]
	v_lshl_add_u32 v32, v32, 9, v208
	v_readlane_b32 s10, v97, s34
	v_readlane_b32 s11, v97, s35
	s_or_b32 s31, s24, 22
	s_or_b32 s33, s24, 23
	v_pk_fma_f32 v[68:69], v[132:133], v[70:71], v[68:69]
	v_cvt_scalef32_pk_f32_fp4 v[70:71], v2, 1.0 op_sel:[0,1,0]
	v_lshl_add_u32 v34, v34, 9, v208
	global_load_dwordx4 v[60:63], v32, s[80:81]
	global_load_dwordx4 v[56:59], v34, s[80:81]
	v_mov_b32_e32 v32, s11
	v_mov_b32_e32 v33, s10
	v_readlane_b32 s10, v97, s31
	v_readlane_b32 s11, v97, s33
	v_pk_fma_f32 v[66:67], v[134:135], v[70:71], v[66:67]
	v_cvt_scalef32_pk_f32_fp4 v[70:71], v2, 1.0 op_sel:[1,1,0]
	v_cndmask_b32_e64 v32, v32, v33, s[0:1]
	v_mov_b32_e32 v34, s11
	v_mov_b32_e32 v35, s10
	v_pk_fma_f32 v[68:69], v[136:137], v[70:71], v[68:69]
	v_cvt_scalef32_pk_f32_fp4 v[70:71], v3, 1.0
	v_cndmask_b32_e64 v34, v34, v35, s[0:1]
	v_pk_fma_f32 v[66:67], v[138:139], v[70:71], v[66:67]
	v_cvt_scalef32_pk_f32_fp4 v[70:71], v3, 1.0 op_sel:[1,0,0]
	s_or_b32 s29, s24, 24
	s_or_b32 s30, s24, 25
	v_pk_fma_f32 v[68:69], v[140:141], v[70:71], v[68:69]
	v_cvt_scalef32_pk_f32_fp4 v[70:71], v3, 1.0 op_sel:[0,1,0]
	v_lshl_add_u32 v32, v32, 9, v208
	v_readlane_b32 s10, v97, s29
	v_readlane_b32 s11, v97, s30
	s_or_b32 s27, s24, 26
	s_or_b32 s28, s24, 27
	v_pk_fma_f32 v[66:67], v[142:143], v[70:71], v[66:67]
	v_cvt_scalef32_pk_f32_fp4 v[70:71], v3, 1.0 op_sel:[1,1,0]
	v_lshl_add_u32 v34, v34, 9, v208
	global_load_dwordx4 v[52:55], v32, s[80:81]
	global_load_dwordx4 v[48:51], v34, s[80:81]
	v_mov_b32_e32 v32, s11
	v_mov_b32_e32 v33, s10
	v_readlane_b32 s10, v97, s27
	v_readlane_b32 s11, v97, s28
	v_pk_fma_f32 v[68:69], v[144:145], v[70:71], v[68:69]
	v_cndmask_b32_e64 v32, v32, v33, s[0:1]
	v_mov_b32_e32 v34, s11
	v_mov_b32_e32 v35, s10
	v_pk_add_f32 v[66:67], v[66:67], v[68:69]
	v_cndmask_b32_e64 v34, v34, v35, s[0:1]
	v_add_f32_e32 v66, v66, v67
	s_or_b32 s25, s24, 28
	s_or_b32 s26, s24, 29
	v_add_f32_dpp v66, v66, v66 quad_perm:[1,0,3,2] row_mask:0xf bank_mask:0xf bound_ctrl:1
	v_lshl_add_u32 v32, v32, 9, v208
	v_readlane_b32 s10, v97, s25
	v_readlane_b32 s11, v97, s26
	v_add_f32_dpp v66, v66, v66 quad_perm:[2,3,0,1] row_mask:0xf bank_mask:0xf bound_ctrl:1
	v_lshl_add_u32 v34, v34, 9, v208
	global_load_dwordx4 v[44:47], v32, s[80:81]
	global_load_dwordx4 v[40:43], v34, s[80:81]
	v_mov_b32_e32 v32, s11
	v_mov_b32_e32 v33, s10
	s_or_b32 s11, s24, 30
	s_or_b32 s10, s24, 31
	v_add_f32_dpp v66, v66, v66 row_half_mirror row_mask:0xf bank_mask:0xf bound_ctrl:1
	v_readlane_b32 s40, v97, s11
	v_readlane_b32 s41, v97, s10
	v_add_f32_dpp v66, v66, v66 row_mirror row_mask:0xf bank_mask:0xf bound_ctrl:1
	v_mov_b32_e32 v35, s40
	v_mov_b32_e32 v34, s41
	v_readlane_b32 s40, v66, 0
	v_readlane_b32 s41, v66, 16
	v_readlane_b32 s42, v66, 32
	v_readlane_b32 s43, v66, 48
	s_waitcnt vmcnt(12)
	v_cvt_scalef32_pk_f32_fp4 v[66:67], v4, 1.0
	v_pk_fma_f32 v[66:67], v[114:115], v[66:67], 0 op_sel_hi:[1,1,0]
	v_cvt_scalef32_pk_f32_fp4 v[68:69], v4, 1.0 op_sel:[1,0,0]
	v_cvt_scalef32_pk_f32_fp4 v[70:71], v4, 1.0 op_sel:[0,1,0]
	v_pk_fma_f32 v[68:69], v[116:117], v[68:69], 0 op_sel_hi:[1,1,0]
	v_pk_fma_f32 v[66:67], v[118:119], v[70:71], v[66:67]
	v_cvt_scalef32_pk_f32_fp4 v[70:71], v4, 1.0 op_sel:[1,1,0]
	v_pk_fma_f32 v[68:69], v[120:121], v[70:71], v[68:69]
	v_cvt_scalef32_pk_f32_fp4 v[70:71], v5, 1.0
	v_pk_fma_f32 v[66:67], v[122:123], v[70:71], v[66:67]
	v_cvt_scalef32_pk_f32_fp4 v[70:71], v5, 1.0 op_sel:[1,0,0]
	v_pk_fma_f32 v[68:69], v[124:125], v[70:71], v[68:69]
	v_cvt_scalef32_pk_f32_fp4 v[70:71], v5, 1.0 op_sel:[0,1,0]
	v_pk_fma_f32 v[66:67], v[126:127], v[70:71], v[66:67]
	v_cvt_scalef32_pk_f32_fp4 v[70:71], v5, 1.0 op_sel:[1,1,0]
	v_pk_fma_f32 v[68:69], v[128:129], v[70:71], v[68:69]
	v_cvt_scalef32_pk_f32_fp4 v[70:71], v6, 1.0
	v_pk_fma_f32 v[66:67], v[130:131], v[70:71], v[66:67]
	v_cvt_scalef32_pk_f32_fp4 v[70:71], v6, 1.0 op_sel:[1,0,0]
	v_pk_fma_f32 v[68:69], v[132:133], v[70:71], v[68:69]
	v_cvt_scalef32_pk_f32_fp4 v[70:71], v6, 1.0 op_sel:[0,1,0]
	v_pk_fma_f32 v[66:67], v[134:135], v[70:71], v[66:67]
	v_cvt_scalef32_pk_f32_fp4 v[70:71], v6, 1.0 op_sel:[1,1,0]
	v_pk_fma_f32 v[68:69], v[136:137], v[70:71], v[68:69]
	v_cvt_scalef32_pk_f32_fp4 v[70:71], v7, 1.0
	v_pk_fma_f32 v[66:67], v[138:139], v[70:71], v[66:67]
	v_cvt_scalef32_pk_f32_fp4 v[70:71], v7, 1.0 op_sel:[1,0,0]
	v_pk_fma_f32 v[68:69], v[140:141], v[70:71], v[68:69]
	v_cvt_scalef32_pk_f32_fp4 v[70:71], v7, 1.0 op_sel:[0,1,0]
	v_pk_fma_f32 v[66:67], v[142:143], v[70:71], v[66:67]
	v_cvt_scalef32_pk_f32_fp4 v[70:71], v7, 1.0 op_sel:[1,1,0]
	v_pk_fma_f32 v[68:69], v[144:145], v[70:71], v[68:69]
	s_waitcnt vmcnt(11)
	v_cvt_scalef32_pk_f32_fp4 v[70:71], v8, 1.0 op_sel:[0,1,0]
	v_pk_add_f32 v[66:67], v[66:67], v[68:69]
	v_cvt_scalef32_pk_f32_fp4 v[68:69], v8, 1.0 op_sel:[1,0,0]
	v_add_f32_e32 v66, v66, v67
	v_pk_fma_f32 v[68:69], v[116:117], v[68:69], 0 op_sel_hi:[1,1,0]
	v_cndmask_b32_e64 v32, v32, v33, s[0:1]
	v_add_f32_dpp v66, v66, v66 quad_perm:[1,0,3,2] row_mask:0xf bank_mask:0xf bound_ctrl:1
	v_cndmask_b32_e64 v34, v34, v35, s[0:1]
	s_nop 0
	v_add_f32_dpp v66, v66, v66 quad_perm:[2,3,0,1] row_mask:0xf bank_mask:0xf bound_ctrl:1
	s_nop 1
	v_add_f32_dpp v66, v66, v66 row_half_mirror row_mask:0xf bank_mask:0xf bound_ctrl:1
	v_lshl_add_u32 v32, v32, 9, v208
	s_nop 0
	v_add_f32_dpp v66, v66, v66 row_mirror row_mask:0xf bank_mask:0xf bound_ctrl:1
	v_lshl_add_u32 v34, v34, 9, v208
	v_readlane_b32 s44, v66, 0
	v_readlane_b32 s45, v66, 16
	v_readlane_b32 s46, v66, 32
	v_readlane_b32 s47, v66, 48
	v_cvt_scalef32_pk_f32_fp4 v[66:67], v8, 1.0
	v_pk_fma_f32 v[66:67], v[114:115], v[66:67], 0 op_sel_hi:[1,1,0]
	global_load_dwordx4 v[36:39], v32, s[80:81]
	s_nop 0
	global_load_dwordx4 v[32:35], v34, s[80:81]
	v_pk_fma_f32 v[66:67], v[118:119], v[70:71], v[66:67]
	v_cvt_scalef32_pk_f32_fp4 v[70:71], v8, 1.0 op_sel:[1,1,0]
	v_pk_fma_f32 v[68:69], v[120:121], v[70:71], v[68:69]
	v_cvt_scalef32_pk_f32_fp4 v[70:71], v9, 1.0
	v_pk_fma_f32 v[66:67], v[122:123], v[70:71], v[66:67]
	v_cvt_scalef32_pk_f32_fp4 v[70:71], v9, 1.0 op_sel:[1,0,0]
	v_pk_fma_f32 v[68:69], v[124:125], v[70:71], v[68:69]
	v_cvt_scalef32_pk_f32_fp4 v[70:71], v9, 1.0 op_sel:[0,1,0]
	v_pk_fma_f32 v[66:67], v[126:127], v[70:71], v[66:67]
	v_cvt_scalef32_pk_f32_fp4 v[70:71], v9, 1.0 op_sel:[1,1,0]
	v_pk_fma_f32 v[68:69], v[128:129], v[70:71], v[68:69]
	v_cvt_scalef32_pk_f32_fp4 v[70:71], v10, 1.0
	v_pk_fma_f32 v[66:67], v[130:131], v[70:71], v[66:67]
	v_cvt_scalef32_pk_f32_fp4 v[70:71], v10, 1.0 op_sel:[1,0,0]
	v_pk_fma_f32 v[68:69], v[132:133], v[70:71], v[68:69]
	v_cvt_scalef32_pk_f32_fp4 v[70:71], v10, 1.0 op_sel:[0,1,0]
	v_pk_fma_f32 v[66:67], v[134:135], v[70:71], v[66:67]
	v_cvt_scalef32_pk_f32_fp4 v[70:71], v10, 1.0 op_sel:[1,1,0]
	v_pk_fma_f32 v[68:69], v[136:137], v[70:71], v[68:69]
	v_cvt_scalef32_pk_f32_fp4 v[70:71], v11, 1.0
	v_pk_fma_f32 v[66:67], v[138:139], v[70:71], v[66:67]
	v_cvt_scalef32_pk_f32_fp4 v[70:71], v11, 1.0 op_sel:[1,0,0]
	v_pk_fma_f32 v[68:69], v[140:141], v[70:71], v[68:69]
	v_cvt_scalef32_pk_f32_fp4 v[70:71], v11, 1.0 op_sel:[0,1,0]
	v_pk_fma_f32 v[66:67], v[142:143], v[70:71], v[66:67]
	v_cvt_scalef32_pk_f32_fp4 v[70:71], v11, 1.0 op_sel:[1,1,0]
	v_pk_fma_f32 v[68:69], v[144:145], v[70:71], v[68:69]
	s_waitcnt vmcnt(12)
	v_cvt_scalef32_pk_f32_fp4 v[70:71], v12, 1.0 op_sel:[0,1,0]
	v_pk_add_f32 v[66:67], v[66:67], v[68:69]
	v_cvt_scalef32_pk_f32_fp4 v[68:69], v12, 1.0 op_sel:[1,0,0]
	v_add_f32_e32 v66, v66, v67
	v_pk_fma_f32 v[68:69], v[116:117], v[68:69], 0 op_sel_hi:[1,1,0]
	s_and_b64 vcc, exec, s[8:9]
	v_add_f32_dpp v66, v66, v66 quad_perm:[1,0,3,2] row_mask:0xf bank_mask:0xf bound_ctrl:1
	s_nop 1
	v_add_f32_dpp v66, v66, v66 quad_perm:[2,3,0,1] row_mask:0xf bank_mask:0xf bound_ctrl:1
	s_nop 1
	v_add_f32_dpp v66, v66, v66 row_half_mirror row_mask:0xf bank_mask:0xf bound_ctrl:1
	s_nop 1
	v_add_f32_dpp v66, v66, v66 row_mirror row_mask:0xf bank_mask:0xf bound_ctrl:1
	s_nop 0
	v_readlane_b32 s48, v66, 0
	v_readlane_b32 s49, v66, 16
	v_readlane_b32 s50, v66, 32
	v_readlane_b32 s51, v66, 48
	v_cvt_scalef32_pk_f32_fp4 v[66:67], v12, 1.0
	v_pk_fma_f32 v[66:67], v[114:115], v[66:67], 0 op_sel_hi:[1,1,0]
	s_nop 0
	v_pk_fma_f32 v[66:67], v[118:119], v[70:71], v[66:67]
	v_cvt_scalef32_pk_f32_fp4 v[70:71], v12, 1.0 op_sel:[1,1,0]
	v_pk_fma_f32 v[68:69], v[120:121], v[70:71], v[68:69]
	v_cvt_scalef32_pk_f32_fp4 v[70:71], v13, 1.0
	v_pk_fma_f32 v[66:67], v[122:123], v[70:71], v[66:67]
	v_cvt_scalef32_pk_f32_fp4 v[70:71], v13, 1.0 op_sel:[1,0,0]
	v_pk_fma_f32 v[68:69], v[124:125], v[70:71], v[68:69]
	v_cvt_scalef32_pk_f32_fp4 v[70:71], v13, 1.0 op_sel:[0,1,0]
	v_pk_fma_f32 v[66:67], v[126:127], v[70:71], v[66:67]
	v_cvt_scalef32_pk_f32_fp4 v[70:71], v13, 1.0 op_sel:[1,1,0]
	v_pk_fma_f32 v[68:69], v[128:129], v[70:71], v[68:69]
	v_cvt_scalef32_pk_f32_fp4 v[70:71], v14, 1.0
	v_pk_fma_f32 v[66:67], v[130:131], v[70:71], v[66:67]
	v_cvt_scalef32_pk_f32_fp4 v[70:71], v14, 1.0 op_sel:[1,0,0]
	v_pk_fma_f32 v[68:69], v[132:133], v[70:71], v[68:69]
	v_cvt_scalef32_pk_f32_fp4 v[70:71], v14, 1.0 op_sel:[0,1,0]
	v_pk_fma_f32 v[66:67], v[134:135], v[70:71], v[66:67]
	v_cvt_scalef32_pk_f32_fp4 v[70:71], v14, 1.0 op_sel:[1,1,0]
	v_pk_fma_f32 v[68:69], v[136:137], v[70:71], v[68:69]
	v_cvt_scalef32_pk_f32_fp4 v[70:71], v15, 1.0
	v_pk_fma_f32 v[66:67], v[138:139], v[70:71], v[66:67]
	v_cvt_scalef32_pk_f32_fp4 v[70:71], v15, 1.0 op_sel:[1,0,0]
	v_pk_fma_f32 v[68:69], v[140:141], v[70:71], v[68:69]
	v_cvt_scalef32_pk_f32_fp4 v[70:71], v15, 1.0 op_sel:[0,1,0]
	v_pk_fma_f32 v[66:67], v[142:143], v[70:71], v[66:67]
	v_cvt_scalef32_pk_f32_fp4 v[70:71], v15, 1.0 op_sel:[1,1,0]
	v_pk_fma_f32 v[68:69], v[144:145], v[70:71], v[68:69]
	s_waitcnt vmcnt(11)
	v_cvt_scalef32_pk_f32_fp4 v[70:71], v16, 1.0 op_sel:[0,1,0]
	v_pk_add_f32 v[66:67], v[66:67], v[68:69]
	v_cvt_scalef32_pk_f32_fp4 v[68:69], v16, 1.0 op_sel:[1,0,0]
	v_add_f32_e32 v66, v66, v67
	v_pk_fma_f32 v[68:69], v[116:117], v[68:69], 0 op_sel_hi:[1,1,0]
	s_nop 0
	v_add_f32_dpp v66, v66, v66 quad_perm:[1,0,3,2] row_mask:0xf bank_mask:0xf bound_ctrl:1
	s_nop 1
	v_add_f32_dpp v66, v66, v66 quad_perm:[2,3,0,1] row_mask:0xf bank_mask:0xf bound_ctrl:1
	s_nop 1
	v_add_f32_dpp v66, v66, v66 row_half_mirror row_mask:0xf bank_mask:0xf bound_ctrl:1
	s_nop 1
	v_add_f32_dpp v66, v66, v66 row_mirror row_mask:0xf bank_mask:0xf bound_ctrl:1
	s_nop 0
	v_readlane_b32 s52, v66, 0
	v_readlane_b32 s53, v66, 16
	v_readlane_b32 s54, v66, 32
	v_readlane_b32 s55, v66, 48
	v_cvt_scalef32_pk_f32_fp4 v[66:67], v16, 1.0
	v_pk_fma_f32 v[66:67], v[114:115], v[66:67], 0 op_sel_hi:[1,1,0]
	s_nop 0
	v_pk_fma_f32 v[66:67], v[118:119], v[70:71], v[66:67]
	v_cvt_scalef32_pk_f32_fp4 v[70:71], v16, 1.0 op_sel:[1,1,0]
	v_pk_fma_f32 v[68:69], v[120:121], v[70:71], v[68:69]
	v_cvt_scalef32_pk_f32_fp4 v[70:71], v17, 1.0
	v_pk_fma_f32 v[66:67], v[122:123], v[70:71], v[66:67]
	v_cvt_scalef32_pk_f32_fp4 v[70:71], v17, 1.0 op_sel:[1,0,0]
	v_pk_fma_f32 v[68:69], v[124:125], v[70:71], v[68:69]
	v_cvt_scalef32_pk_f32_fp4 v[70:71], v17, 1.0 op_sel:[0,1,0]
	v_pk_fma_f32 v[66:67], v[126:127], v[70:71], v[66:67]
	v_cvt_scalef32_pk_f32_fp4 v[70:71], v17, 1.0 op_sel:[1,1,0]
	v_pk_fma_f32 v[68:69], v[128:129], v[70:71], v[68:69]
	v_cvt_scalef32_pk_f32_fp4 v[70:71], v18, 1.0
	v_pk_fma_f32 v[66:67], v[130:131], v[70:71], v[66:67]
	v_cvt_scalef32_pk_f32_fp4 v[70:71], v18, 1.0 op_sel:[1,0,0]
	v_pk_fma_f32 v[68:69], v[132:133], v[70:71], v[68:69]
	v_cvt_scalef32_pk_f32_fp4 v[70:71], v18, 1.0 op_sel:[0,1,0]
	v_pk_fma_f32 v[66:67], v[134:135], v[70:71], v[66:67]
	v_cvt_scalef32_pk_f32_fp4 v[70:71], v18, 1.0 op_sel:[1,1,0]
	v_pk_fma_f32 v[68:69], v[136:137], v[70:71], v[68:69]
	v_cvt_scalef32_pk_f32_fp4 v[70:71], v19, 1.0
	v_pk_fma_f32 v[66:67], v[138:139], v[70:71], v[66:67]
	v_cvt_scalef32_pk_f32_fp4 v[70:71], v19, 1.0 op_sel:[1,0,0]
	v_pk_fma_f32 v[68:69], v[140:141], v[70:71], v[68:69]
	v_cvt_scalef32_pk_f32_fp4 v[70:71], v19, 1.0 op_sel:[0,1,0]
	v_pk_fma_f32 v[66:67], v[142:143], v[70:71], v[66:67]
	v_cvt_scalef32_pk_f32_fp4 v[70:71], v19, 1.0 op_sel:[1,1,0]
	v_pk_fma_f32 v[68:69], v[144:145], v[70:71], v[68:69]
	s_waitcnt vmcnt(10)
	v_cvt_scalef32_pk_f32_fp4 v[70:71], v20, 1.0 op_sel:[0,1,0]
	v_pk_add_f32 v[66:67], v[66:67], v[68:69]
	v_cvt_scalef32_pk_f32_fp4 v[68:69], v20, 1.0 op_sel:[1,0,0]
	v_add_f32_e32 v66, v66, v67
	v_pk_fma_f32 v[68:69], v[116:117], v[68:69], 0 op_sel_hi:[1,1,0]
	s_nop 0
	v_add_f32_dpp v66, v66, v66 quad_perm:[1,0,3,2] row_mask:0xf bank_mask:0xf bound_ctrl:1
	s_nop 1
	v_add_f32_dpp v66, v66, v66 quad_perm:[2,3,0,1] row_mask:0xf bank_mask:0xf bound_ctrl:1
	s_nop 1
	v_add_f32_dpp v66, v66, v66 row_half_mirror row_mask:0xf bank_mask:0xf bound_ctrl:1
	s_nop 1
	v_add_f32_dpp v66, v66, v66 row_mirror row_mask:0xf bank_mask:0xf bound_ctrl:1
	s_nop 0
	v_readlane_b32 s56, v66, 0
	v_readlane_b32 s57, v66, 16
	v_readlane_b32 s62, v66, 32
	v_readlane_b32 s63, v66, 48
	v_cvt_scalef32_pk_f32_fp4 v[66:67], v20, 1.0
	v_pk_fma_f32 v[66:67], v[114:115], v[66:67], 0 op_sel_hi:[1,1,0]
	s_nop 0
	v_pk_fma_f32 v[66:67], v[118:119], v[70:71], v[66:67]
	v_cvt_scalef32_pk_f32_fp4 v[70:71], v20, 1.0 op_sel:[1,1,0]
	v_pk_fma_f32 v[68:69], v[120:121], v[70:71], v[68:69]
	v_cvt_scalef32_pk_f32_fp4 v[70:71], v21, 1.0
	v_pk_fma_f32 v[66:67], v[122:123], v[70:71], v[66:67]
	v_cvt_scalef32_pk_f32_fp4 v[70:71], v21, 1.0 op_sel:[1,0,0]
	v_pk_fma_f32 v[68:69], v[124:125], v[70:71], v[68:69]
	v_cvt_scalef32_pk_f32_fp4 v[70:71], v21, 1.0 op_sel:[0,1,0]
	v_pk_fma_f32 v[66:67], v[126:127], v[70:71], v[66:67]
	v_cvt_scalef32_pk_f32_fp4 v[70:71], v21, 1.0 op_sel:[1,1,0]
	v_pk_fma_f32 v[68:69], v[128:129], v[70:71], v[68:69]
	v_cvt_scalef32_pk_f32_fp4 v[70:71], v22, 1.0
	v_pk_fma_f32 v[66:67], v[130:131], v[70:71], v[66:67]
	v_cvt_scalef32_pk_f32_fp4 v[70:71], v22, 1.0 op_sel:[1,0,0]
	v_pk_fma_f32 v[68:69], v[132:133], v[70:71], v[68:69]
	v_cvt_scalef32_pk_f32_fp4 v[70:71], v22, 1.0 op_sel:[0,1,0]
	v_pk_fma_f32 v[66:67], v[134:135], v[70:71], v[66:67]
	v_cvt_scalef32_pk_f32_fp4 v[70:71], v22, 1.0 op_sel:[1,1,0]
	v_pk_fma_f32 v[68:69], v[136:137], v[70:71], v[68:69]
	v_cvt_scalef32_pk_f32_fp4 v[70:71], v23, 1.0
	v_pk_fma_f32 v[66:67], v[138:139], v[70:71], v[66:67]
	v_cvt_scalef32_pk_f32_fp4 v[70:71], v23, 1.0 op_sel:[1,0,0]
	v_pk_fma_f32 v[68:69], v[140:141], v[70:71], v[68:69]
	v_cvt_scalef32_pk_f32_fp4 v[70:71], v23, 1.0 op_sel:[0,1,0]
	v_pk_fma_f32 v[66:67], v[142:143], v[70:71], v[66:67]
	v_cvt_scalef32_pk_f32_fp4 v[70:71], v23, 1.0 op_sel:[1,1,0]
	v_pk_fma_f32 v[68:69], v[144:145], v[70:71], v[68:69]
	s_waitcnt vmcnt(9)
	v_cvt_scalef32_pk_f32_fp4 v[70:71], v24, 1.0 op_sel:[0,1,0]
	v_pk_add_f32 v[66:67], v[66:67], v[68:69]
	v_cvt_scalef32_pk_f32_fp4 v[68:69], v24, 1.0 op_sel:[1,0,0]
	v_add_f32_e32 v66, v66, v67
	v_pk_fma_f32 v[68:69], v[116:117], v[68:69], 0 op_sel_hi:[1,1,0]
	s_nop 0
	v_add_f32_dpp v66, v66, v66 quad_perm:[1,0,3,2] row_mask:0xf bank_mask:0xf bound_ctrl:1
	s_nop 1
	v_add_f32_dpp v66, v66, v66 quad_perm:[2,3,0,1] row_mask:0xf bank_mask:0xf bound_ctrl:1
	s_nop 1
	v_add_f32_dpp v66, v66, v66 row_half_mirror row_mask:0xf bank_mask:0xf bound_ctrl:1
	s_nop 1
	v_add_f32_dpp v66, v66, v66 row_mirror row_mask:0xf bank_mask:0xf bound_ctrl:1
	s_nop 0
	v_readlane_b32 s65, v66, 0
	v_readlane_b32 s66, v66, 16
	v_readlane_b32 s67, v66, 32
	v_readlane_b32 s68, v66, 48
	v_cvt_scalef32_pk_f32_fp4 v[66:67], v24, 1.0
	v_pk_fma_f32 v[66:67], v[114:115], v[66:67], 0 op_sel_hi:[1,1,0]
	s_nop 0
	v_pk_fma_f32 v[66:67], v[118:119], v[70:71], v[66:67]
	v_cvt_scalef32_pk_f32_fp4 v[70:71], v24, 1.0 op_sel:[1,1,0]
	v_pk_fma_f32 v[68:69], v[120:121], v[70:71], v[68:69]
	v_cvt_scalef32_pk_f32_fp4 v[70:71], v25, 1.0
	v_pk_fma_f32 v[66:67], v[122:123], v[70:71], v[66:67]
	v_cvt_scalef32_pk_f32_fp4 v[70:71], v25, 1.0 op_sel:[1,0,0]
	v_pk_fma_f32 v[68:69], v[124:125], v[70:71], v[68:69]
	v_cvt_scalef32_pk_f32_fp4 v[70:71], v25, 1.0 op_sel:[0,1,0]
	v_pk_fma_f32 v[66:67], v[126:127], v[70:71], v[66:67]
	v_cvt_scalef32_pk_f32_fp4 v[70:71], v25, 1.0 op_sel:[1,1,0]
	v_pk_fma_f32 v[68:69], v[128:129], v[70:71], v[68:69]
	v_cvt_scalef32_pk_f32_fp4 v[70:71], v26, 1.0
	v_pk_fma_f32 v[66:67], v[130:131], v[70:71], v[66:67]
	v_cvt_scalef32_pk_f32_fp4 v[70:71], v26, 1.0 op_sel:[1,0,0]
	v_pk_fma_f32 v[68:69], v[132:133], v[70:71], v[68:69]
	v_cvt_scalef32_pk_f32_fp4 v[70:71], v26, 1.0 op_sel:[0,1,0]
	v_pk_fma_f32 v[66:67], v[134:135], v[70:71], v[66:67]
	v_cvt_scalef32_pk_f32_fp4 v[70:71], v26, 1.0 op_sel:[1,1,0]
	v_pk_fma_f32 v[68:69], v[136:137], v[70:71], v[68:69]
	v_cvt_scalef32_pk_f32_fp4 v[70:71], v27, 1.0
	v_pk_fma_f32 v[66:67], v[138:139], v[70:71], v[66:67]
	v_cvt_scalef32_pk_f32_fp4 v[70:71], v27, 1.0 op_sel:[1,0,0]
	v_pk_fma_f32 v[68:69], v[140:141], v[70:71], v[68:69]
	v_cvt_scalef32_pk_f32_fp4 v[70:71], v27, 1.0 op_sel:[0,1,0]
	v_pk_fma_f32 v[66:67], v[142:143], v[70:71], v[66:67]
	v_cvt_scalef32_pk_f32_fp4 v[70:71], v27, 1.0 op_sel:[1,1,0]
	v_pk_fma_f32 v[68:69], v[144:145], v[70:71], v[68:69]
	s_waitcnt vmcnt(8)
	v_cvt_scalef32_pk_f32_fp4 v[70:71], v28, 1.0 op_sel:[0,1,0]
	v_pk_add_f32 v[66:67], v[66:67], v[68:69]
	v_cvt_scalef32_pk_f32_fp4 v[68:69], v28, 1.0 op_sel:[1,0,0]
	v_add_f32_e32 v66, v66, v67
	v_pk_fma_f32 v[68:69], v[116:117], v[68:69], 0 op_sel_hi:[1,1,0]
	s_nop 0
	v_add_f32_dpp v66, v66, v66 quad_perm:[1,0,3,2] row_mask:0xf bank_mask:0xf bound_ctrl:1
	s_nop 1
	v_add_f32_dpp v66, v66, v66 quad_perm:[2,3,0,1] row_mask:0xf bank_mask:0xf bound_ctrl:1
	s_nop 1
	v_add_f32_dpp v66, v66, v66 row_half_mirror row_mask:0xf bank_mask:0xf bound_ctrl:1
	s_nop 1
	v_add_f32_dpp v66, v66, v66 row_mirror row_mask:0xf bank_mask:0xf bound_ctrl:1
	s_nop 0
	v_readlane_b32 s69, v66, 0
	v_readlane_b32 s70, v66, 16
	v_readlane_b32 s71, v66, 32
	v_readlane_b32 s72, v66, 48
	v_cvt_scalef32_pk_f32_fp4 v[66:67], v28, 1.0
	v_pk_fma_f32 v[66:67], v[114:115], v[66:67], 0 op_sel_hi:[1,1,0]
	s_nop 0
	v_pk_fma_f32 v[66:67], v[118:119], v[70:71], v[66:67]
	v_cvt_scalef32_pk_f32_fp4 v[70:71], v28, 1.0 op_sel:[1,1,0]
	v_pk_fma_f32 v[68:69], v[120:121], v[70:71], v[68:69]
	v_cvt_scalef32_pk_f32_fp4 v[70:71], v29, 1.0
	v_pk_fma_f32 v[66:67], v[122:123], v[70:71], v[66:67]
	v_cvt_scalef32_pk_f32_fp4 v[70:71], v29, 1.0 op_sel:[1,0,0]
	v_pk_fma_f32 v[68:69], v[124:125], v[70:71], v[68:69]
	v_cvt_scalef32_pk_f32_fp4 v[70:71], v29, 1.0 op_sel:[0,1,0]
	v_pk_fma_f32 v[66:67], v[126:127], v[70:71], v[66:67]
	v_cvt_scalef32_pk_f32_fp4 v[70:71], v29, 1.0 op_sel:[1,1,0]
	v_pk_fma_f32 v[68:69], v[128:129], v[70:71], v[68:69]
	v_cvt_scalef32_pk_f32_fp4 v[70:71], v30, 1.0
	v_pk_fma_f32 v[66:67], v[130:131], v[70:71], v[66:67]
	v_cvt_scalef32_pk_f32_fp4 v[70:71], v30, 1.0 op_sel:[1,0,0]
	v_pk_fma_f32 v[68:69], v[132:133], v[70:71], v[68:69]
	v_cvt_scalef32_pk_f32_fp4 v[70:71], v30, 1.0 op_sel:[0,1,0]
	v_pk_fma_f32 v[66:67], v[134:135], v[70:71], v[66:67]
	v_cvt_scalef32_pk_f32_fp4 v[70:71], v30, 1.0 op_sel:[1,1,0]
	v_pk_fma_f32 v[68:69], v[136:137], v[70:71], v[68:69]
	v_cvt_scalef32_pk_f32_fp4 v[70:71], v31, 1.0
	v_pk_fma_f32 v[66:67], v[138:139], v[70:71], v[66:67]
	v_cvt_scalef32_pk_f32_fp4 v[70:71], v31, 1.0 op_sel:[1,0,0]
	v_pk_fma_f32 v[68:69], v[140:141], v[70:71], v[68:69]
	v_cvt_scalef32_pk_f32_fp4 v[70:71], v31, 1.0 op_sel:[0,1,0]
	v_pk_fma_f32 v[66:67], v[142:143], v[70:71], v[66:67]
	v_cvt_scalef32_pk_f32_fp4 v[70:71], v31, 1.0 op_sel:[1,1,0]
	v_pk_fma_f32 v[68:69], v[144:145], v[70:71], v[68:69]
	s_nop 0
	v_pk_add_f32 v[66:67], v[66:67], v[68:69]
	s_nop 0
	v_add_f32_e32 v66, v66, v67
	s_nop 1
	v_add_f32_dpp v66, v66, v66 quad_perm:[1,0,3,2] row_mask:0xf bank_mask:0xf bound_ctrl:1
	s_nop 1
	v_add_f32_dpp v66, v66, v66 quad_perm:[2,3,0,1] row_mask:0xf bank_mask:0xf bound_ctrl:1
	s_nop 1
	v_add_f32_dpp v66, v66, v66 row_half_mirror row_mask:0xf bank_mask:0xf bound_ctrl:1
	s_nop 1
	v_add_f32_dpp v66, v66, v66 row_mirror row_mask:0xf bank_mask:0xf bound_ctrl:1
	s_nop 0
	v_readlane_b32 s74, v66, 0
	v_readlane_b32 s76, v66, 16
	v_readlane_b32 s73, v66, 32
	v_readlane_b32 s75, v66, 48
	s_cbranch_vccnz .LBB0_387
	v_readlane_b32 s77, v97, 32
	v_readlane_b32 s78, v97, 33
	s_nop 0
	v_mov_b32_e32 v1, s77
	v_mov_b32_e32 v0, s78
	v_readlane_b32 s77, v97, 34
	v_readlane_b32 s78, v97, 35
	v_cndmask_b32_e64 v0, v0, v1, s[0:1]
	v_mov_b32_e32 v3, s77
	v_mov_b32_e32 v2, s78
	v_readlane_b32 s77, v97, 36
	v_readlane_b32 s78, v97, 37
	v_cndmask_b32_e64 v2, v2, v3, s[0:1]
	v_mov_b32_e32 v9, s77
	v_mov_b32_e32 v8, s78
	v_readlane_b32 s77, v97, 38
	v_readlane_b32 s78, v97, 39
	v_cndmask_b32_e64 v8, v8, v9, s[0:1]
	v_mov_b32_e32 v11, s77
	v_mov_b32_e32 v10, s78
	v_readlane_b32 s77, v97, 40
	v_readlane_b32 s78, v97, 41
	v_cndmask_b32_e64 v10, v10, v11, s[0:1]
	v_mov_b32_e32 v17, s77
	v_mov_b32_e32 v16, s78
	v_readlane_b32 s77, v97, 42
	v_readlane_b32 s78, v97, 43
	v_cndmask_b32_e64 v16, v16, v17, s[0:1]
	v_mov_b32_e32 v19, s77
	v_mov_b32_e32 v18, s78
	v_readlane_b32 s77, v97, 44
	v_readlane_b32 s78, v97, 45
	v_cndmask_b32_e64 v18, v18, v19, s[0:1]
	v_mov_b32_e32 v25, s77
	v_mov_b32_e32 v24, s78
	v_readlane_b32 s77, v97, 46
	v_readlane_b32 s78, v97, 47
	v_cndmask_b32_e64 v24, v24, v25, s[0:1]
	v_mov_b32_e32 v27, s77
	v_mov_b32_e32 v26, s78
	v_cndmask_b32_e64 v26, v26, v27, s[0:1]
	v_lshl_add_u32 v0, v0, 9, v208
	v_lshl_add_u32 v4, v2, 9, v208
	v_lshl_add_u32 v8, v8, 9, v208
	v_lshl_add_u32 v12, v10, 9, v208
	v_lshl_add_u32 v16, v16, 9, v208
	v_lshl_add_u32 v20, v18, 9, v208
	v_lshl_add_u32 v24, v24, 9, v208
	v_lshl_add_u32 v28, v26, 9, v208
	global_load_dwordx4 v[0:3], v0, s[80:81]
	s_nop 0
	global_load_dwordx4 v[4:7], v4, s[80:81]
	s_nop 0
	global_load_dwordx4 v[8:11], v8, s[80:81]
	s_nop 0
	global_load_dwordx4 v[12:15], v12, s[80:81]
	s_nop 0
	global_load_dwordx4 v[16:19], v16, s[80:81]
	s_nop 0
	global_load_dwordx4 v[20:23], v20, s[80:81]
	s_nop 0
	global_load_dwordx4 v[24:27], v24, s[80:81]
	s_nop 0
	global_load_dwordx4 v[28:31], v28, s[80:81]
	s_branch .LBB0_387

.LBB0_392:
	s_andn2_saveexec_b64 s[8:9], s[8:9]
	v_mul_f32_e32 v2, v1, v1
	v_fmamk_f32 v3, v2, 0xba1345e1, v187
	v_fmaak_f32 v3, v2, v3, 0xbcdac9b8
	v_fmaak_f32 v3, v2, v3, 0x3de703be
	v_fmaak_f32 v3, v2, v3, 0xbec09330
	v_fmaak_f32 v2, v2, v3, 0x3e0375d0
	v_fma_f32 v2, |v1|, v2, |v1|
	s_or_b64 exec, exec, s[8:9]
	v_readlane_b32 s8, v97, 0
	v_readlane_b32 s9, v97, 1
	v_bfi_b32 v1, s22, v2, v1
	v_mov_b32_e32 v4, s8
	v_mov_b32_e32 v3, s9
	v_readlane_b32 s8, v97, 2
	v_readlane_b32 s9, v97, 3
	v_cndmask_b32_e64 v4, v3, v4, s[0:1]
	v_mov_b32_e32 v6, s8
	v_mov_b32_e32 v3, s9
	v_cndmask_b32_e64 v6, v3, v6, s[0:1]
	v_lshl_add_u32 v4, v4, 9, v209
	v_readlane_b32 s8, v97, 4
	v_readlane_b32 s9, v97, 5
	v_lshl_add_u32 v6, v6, 9, v209
	global_load_dwordx4 v[92:95], v4, s[80:81]
	global_load_dwordx4 v[84:87], v6, s[80:81]
	v_mov_b32_e32 v3, s9
	v_mov_b32_e32 v4, s8
	v_readlane_b32 s8, v97, 6
	v_readlane_b32 s9, v97, 7
	v_cndmask_b32_e64 v4, v3, v4, s[0:1]
	v_mov_b32_e32 v6, s8
	v_mov_b32_e32 v3, s9
	v_cndmask_b32_e64 v6, v3, v6, s[0:1]
	v_lshl_add_u32 v4, v4, 9, v209
	v_readlane_b32 s8, v97, 8
	v_readlane_b32 s9, v97, 9
	v_lshl_add_u32 v6, v6, 9, v209
	global_load_dwordx4 v[80:83], v4, s[80:81]
	global_load_dwordx4 v[68:71], v6, s[80:81]
	v_mov_b32_e32 v3, s9
	v_mov_b32_e32 v4, s8
	v_readlane_b32 s8, v97, 10
	v_readlane_b32 s9, v97, 11
	v_cndmask_b32_e64 v4, v3, v4, s[0:1]
	v_mov_b32_e32 v6, s8
	v_mov_b32_e32 v3, s9
	v_cndmask_b32_e64 v6, v3, v6, s[0:1]
	v_lshl_add_u32 v4, v4, 9, v209
	v_readlane_b32 s8, v97, 12
	v_readlane_b32 s9, v97, 13
	v_lshl_add_u32 v6, v6, 9, v209
	global_load_dwordx4 v[64:67], v4, s[80:81]
	global_load_dwordx4 v[48:51], v6, s[80:81]
	v_mov_b32_e32 v3, s9
	v_mov_b32_e32 v4, s8
	v_readlane_b32 s8, v97, 14
	v_readlane_b32 s9, v97, 15
	v_cndmask_b32_e64 v4, v3, v4, s[0:1]
	v_mov_b32_e32 v6, s8
	v_mov_b32_e32 v3, s9
	v_cndmask_b32_e64 v6, v3, v6, s[0:1]
	v_lshl_add_u32 v4, v4, 9, v209
	v_lshl_add_u32 v6, v6, 9, v209
	global_load_dwordx4 v[40:43], v4, s[80:81]
	global_load_dwordx4 v[20:23], v6, s[80:81]
	v_mul_f32_e32 v0, 0.5, v0
	v_add_f32_e32 v1, 1.0, v1
	v_mul_f32_e32 v0, v0, v1
	v_mul_f32_e32 v98, v72, v0
	s_mov_b32 s49, 0
	s_mov_b64 s[10:11], -1
.LBB0_395:
	s_or_b32 s39, s49, 16
	s_or_b32 s40, s49, 17
	v_readlane_b32 s8, v97, s39
	v_readlane_b32 s9, v97, s40
	s_or_b32 s37, s49, 18
	s_or_b32 s38, s49, 19
	v_mov_b32_e32 v0, s9
	v_mov_b32_e32 v1, s8
	v_readlane_b32 s8, v97, s37
	v_readlane_b32 s9, v97, s38
	v_cndmask_b32_e64 v0, v0, v1, s[0:1]
	v_mov_b32_e32 v3, s8
	v_mov_b32_e32 v2, s9
	v_cndmask_b32_e64 v2, v2, v3, s[0:1]
	s_or_b32 s35, s49, 20
	s_or_b32 s36, s49, 21
	v_lshl_add_u32 v0, v0, 9, v209
	v_readlane_b32 s8, v97, s35
	v_readlane_b32 s9, v97, s36
	s_or_b32 s33, s49, 22
	s_or_b32 s34, s49, 23
	v_lshl_add_u32 v2, v2, 9, v209
	global_load_dwordx4 v[88:91], v0, s[80:81]
	global_load_dwordx4 v[76:79], v2, s[80:81]
	v_mov_b32_e32 v0, s9
	v_mov_b32_e32 v1, s8
	v_readlane_b32 s8, v97, s33
	v_readlane_b32 s9, v97, s34
	v_cndmask_b32_e64 v0, v0, v1, s[0:1]
	v_mov_b32_e32 v3, s8
	v_mov_b32_e32 v2, s9
	v_cndmask_b32_e64 v2, v2, v3, s[0:1]
	s_or_b32 s30, s49, 24
	s_or_b32 s31, s49, 25
	v_lshl_add_u32 v0, v0, 9, v209
	v_readlane_b32 s8, v97, s30
	v_readlane_b32 s9, v97, s31
	s_or_b32 s28, s49, 26
	s_or_b32 s29, s49, 27
	v_lshl_add_u32 v2, v2, 9, v209
	global_load_dwordx4 v[72:75], v0, s[80:81]
	global_load_dwordx4 v[56:59], v2, s[80:81]
	v_mov_b32_e32 v0, s9
	v_mov_b32_e32 v1, s8
	v_readlane_b32 s8, v97, s28
	v_readlane_b32 s9, v97, s29
	v_cndmask_b32_e64 v0, v0, v1, s[0:1]
	v_mov_b32_e32 v3, s8
	v_mov_b32_e32 v2, s9
	v_cndmask_b32_e64 v2, v2, v3, s[0:1]
	s_or_b32 s26, s49, 28
	s_or_b32 s27, s49, 29
	v_lshl_add_u32 v0, v0, 9, v209
	v_readlane_b32 s8, v97, s26
	v_readlane_b32 s9, v97, s27
	s_or_b32 s24, s49, 30
	s_or_b32 s25, s49, 31
	v_lshl_add_u32 v2, v2, 9, v209
	global_load_dwordx4 v[44:47], v0, s[80:81]
	global_load_dwordx4 v[16:19], v2, s[80:81]
	v_mov_b32_e32 v0, s9
	v_mov_b32_e32 v1, s8
	v_readlane_b32 s8, v97, s24
	v_readlane_b32 s9, v97, s25
	v_cndmask_b32_e64 v0, v0, v1, s[0:1]
	v_mov_b32_e32 v3, s8
	v_mov_b32_e32 v2, s9
	v_cndmask_b32_e64 v2, v2, v3, s[0:1]
	v_lshl_add_u32 v0, v0, 9, v209
	v_lshl_add_u32 v2, v2, 9, v209
	global_load_dwordx4 v[12:15], v0, s[80:81]
	s_nop 0
	global_load_dwordx4 v[0:3], v2, s[80:81]
	s_xor_b64 s[8:9], s[10:11], -1
	s_or_b32 s10, s49, 1
	v_readlane_b32 s55, v98, s10
	s_or_b32 s10, s49, 2
	v_readlane_b32 s52, v98, s10
	s_or_b32 s10, s49, 3
	v_readlane_b32 s53, v98, s10
	s_or_b32 s10, s49, 4
	v_readlane_b32 s50, v98, s10
	s_or_b32 s10, s49, 5
	v_readlane_b32 s51, v98, s10
	s_or_b32 s10, s49, 6
	v_readlane_b32 s47, v98, s10
	s_or_b32 s10, s49, 7
	v_readlane_b32 s48, v98, s10
	s_or_b32 s10, s49, 8
	v_readlane_b32 s45, v98, s10
	s_or_b32 s10, s49, 9
	v_readlane_b32 s46, v98, s10
	s_or_b32 s10, s49, 10
	v_readlane_b32 s43, v98, s10
	s_or_b32 s10, s49, 11
	v_readlane_b32 s44, v98, s10
	s_or_b32 s10, s49, 12
	v_readlane_b32 s41, v98, s10
	s_or_b32 s10, s49, 13
	v_readlane_b32 s42, v98, s10
	s_or_b32 s10, s49, 14
	s_or_b32 s11, s49, 15
	v_readlane_b32 s54, v98, s49
	v_readlane_b32 s10, v98, s10
	v_readlane_b32 s11, v98, s11
	s_and_b64 vcc, exec, s[8:9]
	s_waitcnt vmcnt(15)
	v_mov_b32_e32 v4, v92
	v_mov_b32_e32 v5, v93
	v_mov_b32_e32 v6, v94
	v_mov_b32_e32 v7, v95
	s_waitcnt vmcnt(14)
	v_mov_b32_e32 v8, v84
	v_mov_b32_e32 v9, v85
	v_mov_b32_e32 v10, v86
	v_mov_b32_e32 v11, v87
	s_waitcnt vmcnt(13)
	v_mov_b32_e32 v24, v80
	v_mov_b32_e32 v25, v81
	v_mov_b32_e32 v26, v82
	v_mov_b32_e32 v27, v83
	s_waitcnt vmcnt(12)
	v_mov_b32_e32 v28, v68
	v_mov_b32_e32 v29, v69
	v_mov_b32_e32 v30, v70
	v_mov_b32_e32 v31, v71
	s_waitcnt vmcnt(11)
	v_mov_b32_e32 v32, v64
	v_mov_b32_e32 v33, v65
	v_mov_b32_e32 v34, v66
	v_mov_b32_e32 v35, v67
	s_waitcnt vmcnt(10)
	v_mov_b32_e32 v36, v48
	v_mov_b32_e32 v37, v49
	v_mov_b32_e32 v38, v50
	v_mov_b32_e32 v39, v51
	s_waitcnt vmcnt(9)
	v_mov_b32_e32 v52, v40
	v_mov_b32_e32 v53, v41
	v_mov_b32_e32 v54, v42
	v_mov_b32_e32 v55, v43
	s_waitcnt vmcnt(8)
	v_mov_b32_e32 v60, v20
	v_mov_b32_e32 v61, v21
	v_mov_b32_e32 v62, v22
	v_mov_b32_e32 v63, v23
	s_cbranch_vccnz .LBB0_397
	v_readlane_b32 s49, v97, 32
	v_readlane_b32 s56, v97, 33
	s_nop 0
	v_mov_b32_e32 v5, s49
	v_mov_b32_e32 v4, s56
	v_readlane_b32 s49, v97, 34
	v_readlane_b32 s56, v97, 35
	v_cndmask_b32_e64 v4, v4, v5, s[0:1]
	v_mov_b32_e32 v7, s49
	v_mov_b32_e32 v6, s56
	v_readlane_b32 s49, v97, 36
	v_readlane_b32 s56, v97, 37
	v_cndmask_b32_e64 v6, v6, v7, s[0:1]
	v_mov_b32_e32 v25, s49
	v_mov_b32_e32 v24, s56
	v_readlane_b32 s49, v97, 38
	v_readlane_b32 s56, v97, 39
	v_cndmask_b32_e64 v24, v24, v25, s[0:1]
	v_mov_b32_e32 v27, s49
	v_mov_b32_e32 v26, s56
	v_readlane_b32 s49, v97, 40
	v_readlane_b32 s56, v97, 41
	v_cndmask_b32_e64 v26, v26, v27, s[0:1]
	v_mov_b32_e32 v33, s49
	v_mov_b32_e32 v32, s56
	v_readlane_b32 s49, v97, 42
	v_readlane_b32 s56, v97, 43
	v_cndmask_b32_e64 v32, v32, v33, s[0:1]
	v_mov_b32_e32 v35, s49
	v_mov_b32_e32 v34, s56
	v_readlane_b32 s49, v97, 44
	v_readlane_b32 s56, v97, 45
	v_cndmask_b32_e64 v34, v34, v35, s[0:1]
	v_mov_b32_e32 v53, s49
	v_mov_b32_e32 v52, s56
	v_readlane_b32 s49, v97, 46
	v_readlane_b32 s56, v97, 47
	v_cndmask_b32_e64 v52, v52, v53, s[0:1]
	v_mov_b32_e32 v55, s49
	v_mov_b32_e32 v54, s56
	v_cndmask_b32_e64 v54, v54, v55, s[0:1]
	v_lshl_add_u32 v4, v4, 9, v209
	v_lshl_add_u32 v8, v6, 9, v209
	v_lshl_add_u32 v24, v24, 9, v209
	v_lshl_add_u32 v28, v26, 9, v209
	v_lshl_add_u32 v32, v32, 9, v209
	v_lshl_add_u32 v36, v34, 9, v209
	v_lshl_add_u32 v52, v52, 9, v209
	v_lshl_add_u32 v60, v54, 9, v209
	global_load_dwordx4 v[4:7], v4, s[80:81]
	s_nop 0
	global_load_dwordx4 v[8:11], v8, s[80:81]
	s_nop 0
	global_load_dwordx4 v[24:27], v24, s[80:81]
	s_nop 0
	global_load_dwordx4 v[28:31], v28, s[80:81]
	s_nop 0
	global_load_dwordx4 v[32:35], v32, s[80:81]
	s_nop 0
	global_load_dwordx4 v[36:39], v36, s[80:81]
	s_nop 0
	global_load_dwordx4 v[52:55], v52, s[80:81]
	s_nop 0
	global_load_dwordx4 v[60:63], v60, s[80:81]
